# code placement pin at 128 bytes: .p2align 7 instead of 6 on the GEMM1, branch and out GEMM main-loop heads
# speedup vs baseline: 1.0020x; 1.0020x over previous
;     __device__ bool next(int i, Unit& u) const { if (i != 0) return false; u.pm = pm; u.pn = pn; return true; }
;     __device__ bool next(int i, Unit& u) const { const int L = i * G + c; if (L >= 256) return false; u.pm = L; u.pn = L >> 6; return true; }
;     __device__ bool next(int i, Unit& u) const { Unit t; if (!so.next(i >> 2, t)) return false; const int b = i & 3; u.pm = b * 64 + t.pm; u.pn = b * 8 + t.pn; return true; }
;     __device__ __forceinline__ bool zero_after(const Unit& u) const { return (u.pm >> 6) == 3; }
; template <bool ALIGN_EPI, bool SP2, class Epi, class Sched>
; __device__ __forceinline__ void gemm_phase(LAS unsigned char* lds, const Gemm g, const Sched& S, const Epi& E) {
;     ...
;         const bool has_next = S.next(ui + 1, nxt);
;         const char* nA = has_next ? (const char*)g.A + (size_t)nxt.pm * tstep : cA; const char* nB = has_next ? (const char*)g.Bt + (size_t)nxt.pn * tstep : cB;
;         for (int t = 0; t < nt; t += 2) {
;             const bool last = (t == nt - 2);
;             const char* a1 = cA + (size_t)(t + 1) * kstep;
;             const char* a2 = last ? nA : cA + (size_t)(t + 2) * kstep; const char* b2 = last ? nB : cB + (size_t)(t + 2) * kstep;
;             const char* a3 = a2 + kstep; const char* b3 = b2 + kstep;
;     ...
;         E(acc, cur, wr, wc, fr, fq);
;         if (!has_next) break;
;         if (E.zero_after(cur))
; #pragma unroll
;         for (int a = 0; a < 2; ++a)
; #pragma unroll
;             for (int b = 0; b < 2; ++b)
; #pragma unroll
;                 for (int m = 0; m < 4; ++m)
; #pragma unroll
;                     for (int n = 0; n < 2; ++n) acc[a][b][m][n] = (f32x4){0.f, 0.f, 0.f, 0.f};
;         cur = nxt; cA = nA; cB = nB; ++ui;
.LBB0_233:
	v_mov_b32_e32 v117, 0
	s_andn2_b64 vcc, exec, s[38:39]
	v_mov_b32_e32 v116, v117
	v_mov_b32_e32 v115, v117
	v_mov_b32_e32 v114, v117
	v_mov_b32_e32 v129, v117
	v_mov_b32_e32 v128, v117
	v_mov_b32_e32 v127, v117
	v_mov_b32_e32 v126, v117
	v_mov_b32_e32 v101, v117
	v_mov_b32_e32 v100, v117
	v_mov_b32_e32 v99, v117
	v_mov_b32_e32 v98, v117
	v_mov_b32_e32 v113, v117
	v_mov_b32_e32 v112, v117
	v_mov_b32_e32 v111, v117
	v_mov_b32_e32 v110, v117
	v_mov_b32_e32 v85, v117
	v_mov_b32_e32 v84, v117
	v_mov_b32_e32 v83, v117
	v_mov_b32_e32 v82, v117
	v_mov_b32_e32 v97, v117
	v_mov_b32_e32 v96, v117
	v_mov_b32_e32 v95, v117
	v_mov_b32_e32 v94, v117
	v_mov_b32_e32 v69, v117
	v_mov_b32_e32 v68, v117
	v_mov_b32_e32 v67, v117
	v_mov_b32_e32 v66, v117
	v_mov_b32_e32 v81, v117
	v_mov_b32_e32 v80, v117
	v_mov_b32_e32 v79, v117
	v_mov_b32_e32 v78, v117
	v_mov_b32_e32 v125, v117
	v_mov_b32_e32 v124, v117
	v_mov_b32_e32 v123, v117
	v_mov_b32_e32 v122, v117
	v_mov_b32_e32 v121, v117
	v_mov_b32_e32 v120, v117
	v_mov_b32_e32 v119, v117
	v_mov_b32_e32 v118, v117
	v_mov_b32_e32 v109, v117
	v_mov_b32_e32 v108, v117
	v_mov_b32_e32 v107, v117
	v_mov_b32_e32 v106, v117
	v_mov_b32_e32 v105, v117
	v_mov_b32_e32 v104, v117
	v_mov_b32_e32 v103, v117
	v_mov_b32_e32 v102, v117
	v_mov_b32_e32 v93, v117
	v_mov_b32_e32 v92, v117
	v_mov_b32_e32 v91, v117
	v_mov_b32_e32 v90, v117
	v_mov_b32_e32 v89, v117
	v_mov_b32_e32 v88, v117
	v_mov_b32_e32 v87, v117
	v_mov_b32_e32 v86, v117
	v_mov_b32_e32 v77, v117
	v_mov_b32_e32 v76, v117
	v_mov_b32_e32 v75, v117
	v_mov_b32_e32 v74, v117
	v_mov_b32_e32 v73, v117
	v_mov_b32_e32 v72, v117
	v_mov_b32_e32 v71, v117
	v_mov_b32_e32 v70, v117
	v_mov_b32_e32 v53, v117
	v_mov_b32_e32 v52, v117
	v_mov_b32_e32 v51, v117
	v_mov_b32_e32 v50, v117
	v_mov_b32_e32 v65, v117
	v_mov_b32_e32 v64, v117
	v_mov_b32_e32 v63, v117
	v_mov_b32_e32 v62, v117
	v_mov_b32_e32 v37, v117
	v_mov_b32_e32 v36, v117
	v_mov_b32_e32 v35, v117
	v_mov_b32_e32 v34, v117
	v_mov_b32_e32 v49, v117
	v_mov_b32_e32 v48, v117
	v_mov_b32_e32 v47, v117
	v_mov_b32_e32 v46, v117
	v_mov_b32_e32 v21, v117
	v_mov_b32_e32 v20, v117
	v_mov_b32_e32 v19, v117
	v_mov_b32_e32 v18, v117
	v_mov_b32_e32 v33, v117
	v_mov_b32_e32 v32, v117
	v_mov_b32_e32 v31, v117
	v_mov_b32_e32 v30, v117
	v_mov_b32_e32 v5, v117
	v_mov_b32_e32 v4, v117
	v_mov_b32_e32 v3, v117
	v_mov_b32_e32 v2, v117
	v_mov_b32_e32 v17, v117
	v_mov_b32_e32 v16, v117
	v_mov_b32_e32 v15, v117
	v_mov_b32_e32 v14, v117
	v_mov_b32_e32 v61, v117
	v_mov_b32_e32 v60, v117
	v_mov_b32_e32 v59, v117
	v_mov_b32_e32 v58, v117
	v_mov_b32_e32 v57, v117
	v_mov_b32_e32 v56, v117
	v_mov_b32_e32 v55, v117
	v_mov_b32_e32 v54, v117
	v_mov_b32_e32 v45, v117
	v_mov_b32_e32 v44, v117
	v_mov_b32_e32 v43, v117
	v_mov_b32_e32 v42, v117
	v_mov_b32_e32 v41, v117
	v_mov_b32_e32 v40, v117
	v_mov_b32_e32 v39, v117
	v_mov_b32_e32 v38, v117
	v_mov_b32_e32 v29, v117
	v_mov_b32_e32 v28, v117
	v_mov_b32_e32 v27, v117
	v_mov_b32_e32 v26, v117
	v_mov_b32_e32 v25, v117
	v_mov_b32_e32 v24, v117
	v_mov_b32_e32 v23, v117
	v_mov_b32_e32 v22, v117
	v_mov_b32_e32 v13, v117
	v_mov_b32_e32 v12, v117
	v_mov_b32_e32 v11, v117
	v_mov_b32_e32 v10, v117
	v_mov_b32_e32 v9, v117
	v_mov_b32_e32 v8, v117
	v_mov_b32_e32 v7, v117
	v_mov_b32_e32 v6, v117
	s_cbranch_vccnz .LBB0_236
	s_add_u32 s42, s90, 0x80
	s_addc_u32 s43, s91, 0
	s_add_u32 s24, s44, 0x100
	v_mov_b32_e32 v6, 0
	s_addc_u32 s71, s45, 0
	s_mov_b32 s44, 0
	.p2align 7

;     __device__ bool next(int i, Unit& u) const { if (i != 0) return false; u.pm = pm; u.pn = pn; return true; }
;     __device__ bool next(int i, Unit& u) const { const int L = i * G + c; if (L >= 256) return false; u.pm = L; u.pn = L >> 6; return true; }
;     __device__ bool next(int i, Unit& u) const { Unit t; if (!so.next(i >> 2, t)) return false; const int b = i & 3; u.pm = b * 64 + t.pm; u.pn = b * 8 + t.pn; return true; }
; template <bool ALIGN_EPI, bool SP2, class Epi, class Sched>
; __device__ __forceinline__ void gemm_phase(LAS unsigned char* lds, const Gemm g, const Sched& S, const Epi& E) {
;     ...
;         const bool has_next = S.next(ui + 1, nxt);
;         const char* nA = has_next ? (const char*)g.A + (size_t)nxt.pm * tstep : cA; const char* nB = has_next ? (const char*)g.Bt + (size_t)nxt.pn * tstep : cB;
;         for (int t = 0; t < nt; t += 2) {
;             const bool last = (t == nt - 2);
;             const char* a1 = cA + (size_t)(t + 1) * kstep;
;             const char* a2 = last ? nA : cA + (size_t)(t + 2) * kstep; const char* b2 = last ? nB : cB + (size_t)(t + 2) * kstep;
;             const char* a3 = a2 + kstep; const char* b3 = b2 + kstep;
;     ...
;         cur = nxt; cA = nA; cB = nB; ++ui;
.LBB0_703:
	s_add_u32 s44, s94, 0x80
	s_addc_u32 s45, s95, 0
	s_add_u32 s92, s92, 0x100
	s_addc_u32 s93, s93, 0
	s_mov_b32 s88, 0
	.p2align 7

;     __device__ bool next(int i, Unit& u) const { if (i != 0) return false; u.pm = pm; u.pn = pn; return true; }
;     __device__ bool next(int i, Unit& u) const { const int L = i * G + c; if (L >= 256) return false; u.pm = L; u.pn = L >> 6; return true; }
;     __device__ bool next(int i, Unit& u) const { Unit t; if (!so.next(i >> 2, t)) return false; const int b = i & 3; u.pm = b * 64 + t.pm; u.pn = b * 8 + t.pn; return true; }
;     __device__ __forceinline__ bool zero_after(const Unit& u) const { return (u.pm >> 6) == 3; }
; template <bool ALIGN_EPI, bool SP2, class Epi, class Sched>
; __device__ __forceinline__ void gemm_phase(LAS unsigned char* lds, const Gemm g, const Sched& S, const Epi& E) {
;     ...
;         const bool has_next = S.next(ui + 1, nxt);
;         const char* nA = has_next ? (const char*)g.A + (size_t)nxt.pm * tstep : cA; const char* nB = has_next ? (const char*)g.Bt + (size_t)nxt.pn * tstep : cB;
;         for (int t = 0; t < nt; t += 2) {
;             const bool last = (t == nt - 2);
;             const char* a1 = cA + (size_t)(t + 1) * kstep;
;             const char* a2 = last ? nA : cA + (size_t)(t + 2) * kstep; const char* b2 = last ? nB : cB + (size_t)(t + 2) * kstep;
;             const char* a3 = a2 + kstep; const char* b3 = b2 + kstep;
;     ...
;         E(acc, cur, wr, wc, fr, fq);
;         if (!has_next) break;
;         if (E.zero_after(cur))
; #pragma unroll
;         for (int a = 0; a < 2; ++a)
; #pragma unroll
;             for (int b = 0; b < 2; ++b)
; #pragma unroll
;                 for (int m = 0; m < 4; ++m)
; #pragma unroll
;                     for (int n = 0; n < 2; ++n) acc[a][b][m][n] = (f32x4){0.f, 0.f, 0.f, 0.f};
;         cur = nxt; cA = nA; cB = nB; ++ui;
.LBB0_833:
	v_mov_b32_e32 v129, 0
	s_andn2_b64 vcc, exec, s[44:45]
	v_mov_b32_e32 v128, v129
	v_mov_b32_e32 v127, v129
	v_mov_b32_e32 v126, v129
	v_mov_b32_e32 v125, v129
	v_mov_b32_e32 v124, v129
	v_mov_b32_e32 v123, v129
	v_mov_b32_e32 v122, v129
	v_mov_b32_e32 v113, v129
	v_mov_b32_e32 v112, v129
	v_mov_b32_e32 v111, v129
	v_mov_b32_e32 v110, v129
	v_mov_b32_e32 v109, v129
	v_mov_b32_e32 v108, v129
	v_mov_b32_e32 v107, v129
	v_mov_b32_e32 v106, v129
	v_mov_b32_e32 v97, v129
	v_mov_b32_e32 v96, v129
	v_mov_b32_e32 v95, v129
	v_mov_b32_e32 v94, v129
	v_mov_b32_e32 v93, v129
	v_mov_b32_e32 v92, v129
	v_mov_b32_e32 v91, v129
	v_mov_b32_e32 v90, v129
	v_mov_b32_e32 v81, v129
	v_mov_b32_e32 v80, v129
	v_mov_b32_e32 v79, v129
	v_mov_b32_e32 v78, v129
	v_mov_b32_e32 v77, v129
	v_mov_b32_e32 v76, v129
	v_mov_b32_e32 v75, v129
	v_mov_b32_e32 v74, v129
	v_mov_b32_e32 v121, v129
	v_mov_b32_e32 v120, v129
	v_mov_b32_e32 v119, v129
	v_mov_b32_e32 v118, v129
	v_mov_b32_e32 v117, v129
	v_mov_b32_e32 v116, v129
	v_mov_b32_e32 v115, v129
	v_mov_b32_e32 v114, v129
	v_mov_b32_e32 v105, v129
	v_mov_b32_e32 v104, v129
	v_mov_b32_e32 v103, v129
	v_mov_b32_e32 v102, v129
	v_mov_b32_e32 v101, v129
	v_mov_b32_e32 v100, v129
	v_mov_b32_e32 v99, v129
	v_mov_b32_e32 v98, v129
	v_mov_b32_e32 v89, v129
	v_mov_b32_e32 v88, v129
	v_mov_b32_e32 v87, v129
	v_mov_b32_e32 v86, v129
	v_mov_b32_e32 v85, v129
	v_mov_b32_e32 v84, v129
	v_mov_b32_e32 v83, v129
	v_mov_b32_e32 v82, v129
	v_mov_b32_e32 v73, v129
	v_mov_b32_e32 v72, v129
	v_mov_b32_e32 v71, v129
	v_mov_b32_e32 v70, v129
	v_mov_b32_e32 v69, v129
	v_mov_b32_e32 v68, v129
	v_mov_b32_e32 v67, v129
	v_mov_b32_e32 v66, v129
	v_mov_b32_e32 v65, v129
	v_mov_b32_e32 v64, v129
	v_mov_b32_e32 v63, v129
	v_mov_b32_e32 v62, v129
	v_mov_b32_e32 v61, v129
	v_mov_b32_e32 v60, v129
	v_mov_b32_e32 v59, v129
	v_mov_b32_e32 v58, v129
	v_mov_b32_e32 v49, v129
	v_mov_b32_e32 v48, v129
	v_mov_b32_e32 v47, v129
	v_mov_b32_e32 v46, v129
	v_mov_b32_e32 v45, v129
	v_mov_b32_e32 v44, v129
	v_mov_b32_e32 v43, v129
	v_mov_b32_e32 v42, v129
	v_mov_b32_e32 v33, v129
	v_mov_b32_e32 v32, v129
	v_mov_b32_e32 v31, v129
	v_mov_b32_e32 v30, v129
	v_mov_b32_e32 v29, v129
	v_mov_b32_e32 v28, v129
	v_mov_b32_e32 v27, v129
	v_mov_b32_e32 v26, v129
	v_mov_b32_e32 v17, v129
	v_mov_b32_e32 v16, v129
	v_mov_b32_e32 v15, v129
	v_mov_b32_e32 v14, v129
	v_mov_b32_e32 v13, v129
	v_mov_b32_e32 v12, v129
	v_mov_b32_e32 v11, v129
	v_mov_b32_e32 v10, v129
	v_mov_b32_e32 v57, v129
	v_mov_b32_e32 v56, v129
	v_mov_b32_e32 v55, v129
	v_mov_b32_e32 v54, v129
	v_mov_b32_e32 v53, v129
	v_mov_b32_e32 v52, v129
	v_mov_b32_e32 v51, v129
	v_mov_b32_e32 v50, v129
	v_mov_b32_e32 v41, v129
	v_mov_b32_e32 v40, v129
	v_mov_b32_e32 v39, v129
	v_mov_b32_e32 v38, v129
	v_mov_b32_e32 v37, v129
	v_mov_b32_e32 v36, v129
	v_mov_b32_e32 v35, v129
	v_mov_b32_e32 v34, v129
	v_mov_b32_e32 v25, v129
	v_mov_b32_e32 v24, v129
	v_mov_b32_e32 v23, v129
	v_mov_b32_e32 v22, v129
	v_mov_b32_e32 v21, v129
	v_mov_b32_e32 v20, v129
	v_mov_b32_e32 v19, v129
	v_mov_b32_e32 v18, v129
	v_mov_b32_e32 v9, v129
	v_mov_b32_e32 v8, v129
	v_mov_b32_e32 v7, v129
	v_mov_b32_e32 v6, v129
	v_mov_b32_e32 v5, v129
	v_mov_b32_e32 v4, v129
	v_mov_b32_e32 v3, v129
	v_mov_b32_e32 v2, v129
	s_cbranch_vccnz .LBB0_836
	s_add_u32 s86, s86, 0x80
	s_addc_u32 s87, s87, 0
	s_add_u32 s24, s90, 0x100
	v_mov_b32_e32 v2, 0
	s_addc_u32 s90, s91, 0
	s_mov_b32 s88, 0
	.p2align 7
